# comb26 + packed-to-scalar split (guide 7.5) of the 8 state-decay v_pk_mul_f32 per chunk that feed the scan's S3a MFMA accumulators
# baseline (speedup 1.0000x reference)
; #define LAS __attribute__((address_space(3)))
; __device__ __forceinline__ unsigned cvt_pk(float lo, float hi) { unsigned r; asm volatile("v_cvt_pk_bf16_f32 %0, %1, %2" : "=v"(r) : "v"(lo), "v"(hi)); return r; }
; __device__ __forceinline__ unsigned f2bf(float f) { unsigned u = __builtin_bit_cast(unsigned, f); return (u + 0x7fffu + ((u >> 16) & 1u)) >> 16; }
; __device__ __forceinline__ void scan_job(LAS unsigned char* lds, int b, int h, int dir, int layer, const bf16_t* P, const float* lbp, bf16_t* xc, bf16_t* ob) {
;     ...
;               for (int r = 0; r < 4; ++r) { const size_t row = dir ? row0 - r : row0 + r;
;                   if (dir == 0) xc[row * DM + 512 + col] = (bf16_t)f2bf(o[r]); else ob[row * 256 + col] = (bf16_t)f2bf(o[r]); } } }
;         { const f32x4 dec = *(const LAS f32x4*)(TOT + 16 * wid + 4 * lq);
;           const LAS unsigned char* ka = lds + S_K4T + (16 * wid + l15) * 144 + lq * 16; const bf16x8 k0 = *(const LAS bf16x8*)(ka), k1 = *(const LAS bf16x8*)(ka + 64);
; #pragma unroll
;           for (int vj = 0; vj < 4; ++vj) { const LAS unsigned char* vb = lds + S_VT + (16 * vj + l15) * 144 + lq * 16;
;               f32x4 a = Sacc[vj] * dec;
;               a = __builtin_amdgcn_mfma_f32_16x16x32_bf16(k0, *(const LAS bf16x8*)(vb), a, 0, 0, 0);
;               a = __builtin_amdgcn_mfma_f32_16x16x32_bf16(k1, *(const LAS bf16x8*)(vb + 64), a, 0, 0, 0);
;               Sacc[vj] = a; } }
;         __syncthreads();
; #pragma unroll
;         for (int vj = 0; vj < 4; ++vj) { u32x2 w; w.x = cvt_pk(Sacc[vj][0], Sacc[vj][1]); w.y = cvt_pk(Sacc[vj][2], Sacc[vj][3]);
;             *(LAS u32x2*)(lds + S_ST + (16 * vj + l15) * 272 + (16 * wid + 4 * lq) * 2) = w; }
.LBB0_622:
	v_lshl_add_u64 v[26:27], v[66:67], 0, s[72:73]
	v_bfe_u32 v22, v23, 16, 1
	v_add3_u32 v28, v23, v22, s92
	v_lshl_add_u64 v[22:23], v[26:27], 0, v[76:77]
	v_lshl_add_u64 v[26:27], v[22:23], 0, s[24:25]
	global_store_short_d16_hi v[26:27], v28, off offset:32
	v_bfe_u32 v26, v24, 16, 1
	v_add3_u32 v24, v24, v26, s92
	v_lshl_add_u64 v[26:27], v[22:23], 0, s[22:23]
	global_store_short_d16_hi v[26:27], v24, off offset:32
	v_bfe_u32 v24, v25, 16, 1
	v_add3_u32 v24, v25, v24, s92
	v_lshl_add_u64 v[22:23], v[22:23], 0, s[20:21]
	global_store_short_d16_hi v[22:23], v24, off offset:32
	ds_read_b128 v[22:25], v108
	ds_read_b128 v[26:29], v119
	ds_read_b128 v[30:33], v119 offset:64
	ds_read_b128 v[34:37], v120
	s_cmp_lg_u32 s97, 36
	s_waitcnt lgkmcnt(3)
	v_mul_f32_e32 v8, v8, v24
	v_mul_f32_e32 v9, v9, v25
	v_mul_f32_e32 v6, v6, v22
	v_mul_f32_e32 v7, v7, v23
	v_mul_f32_e32 v12, v12, v24
	v_mul_f32_e32 v13, v13, v25
	v_mul_f32_e32 v10, v10, v22
	v_mul_f32_e32 v11, v11, v23
	v_mul_f32_e32 v16, v16, v24
	v_mul_f32_e32 v17, v17, v25
	v_mul_f32_e32 v14, v14, v22
	v_mul_f32_e32 v15, v15, v23
	v_mul_f32_e32 v20, v20, v24
	v_mul_f32_e32 v21, v21, v25
	v_mul_f32_e32 v18, v18, v22
	v_mul_f32_e32 v19, v19, v23
	ds_read_b128 v[22:25], v120 offset:6912
	ds_read_b128 v[200:203], v120 offset:64
	ds_read_b128 v[204:207], v120 offset:6976
	ds_read_b128 v[208:211], v120 offset:2304
	ds_read_b128 v[212:215], v120 offset:2368
	ds_read_b128 v[216:219], v120 offset:4608
	ds_read_b128 v[220:223], v120 offset:4672
	s_waitcnt lgkmcnt(7)
	v_mfma_f32_16x16x32_bf16 v[6:9], v[26:29], v[34:37], v[6:9]
	s_waitcnt vmcnt(23)
	v_mov_b32_e32 v47, v122
	s_waitcnt vmcnt(21)
	v_mov_b32_e32 v44, v123
	s_waitcnt lgkmcnt(6)
	v_mfma_f32_16x16x32_bf16 v[18:21], v[26:29], v[22:25], v[18:21]
	s_waitcnt vmcnt(19)
	v_mov_b32_e32 v43, v124
	s_waitcnt vmcnt(17)
	v_mov_b32_e32 v42, v125
	s_waitcnt lgkmcnt(5)
	v_mfma_f32_16x16x32_bf16 v[6:9], v[30:33], v[200:203], v[6:9]
	s_waitcnt vmcnt(15)
	v_mov_b32_e32 v41, v126
	s_waitcnt vmcnt(13)
	v_mov_b32_e32 v40, v127
	s_waitcnt lgkmcnt(3)
	v_mfma_f32_16x16x32_bf16 v[10:13], v[26:29], v[208:211], v[10:13]
	s_waitcnt vmcnt(11)
	v_mov_b32_e32 v39, v128
	s_waitcnt vmcnt(9)
	v_mov_b32_e32 v38, v129
	s_waitcnt lgkmcnt(2)
	v_mfma_f32_16x16x32_bf16 v[10:13], v[30:33], v[212:215], v[10:13]
	s_mov_b32 s72, s97
	s_waitcnt lgkmcnt(1)
	v_mfma_f32_16x16x32_bf16 v[14:17], v[26:29], v[216:219], v[14:17]
	s_waitcnt lgkmcnt(0)
	s_barrier
	v_mfma_f32_16x16x32_bf16 v[14:17], v[30:33], v[220:223], v[14:17]
	v_mfma_f32_16x16x32_bf16 v[18:21], v[30:33], v[204:207], v[18:21]
	v_cvt_pk_bf16_f32 v22, v6, v7
	v_cvt_pk_bf16_f32 v23, v8, v9
	ds_write_b64 v121, v[22:23]
	v_cvt_pk_bf16_f32 v22, v10, v11
	v_cvt_pk_bf16_f32 v23, v12, v13
	ds_write_b64 v121, v[22:23] offset:4352
	v_cvt_pk_bf16_f32 v22, v14, v15
	v_cvt_pk_bf16_f32 v23, v16, v17
	ds_write_b64 v121, v[22:23] offset:8704
	v_cvt_pk_bf16_f32 v22, v18, v19
	v_cvt_pk_bf16_f32 v23, v20, v21
	ds_write_b64 v121, v[22:23] offset:13056
	s_cbranch_scc0 .LBB0_602

; #define LAS __attribute__((address_space(3)))
; __device__ __forceinline__ unsigned cvt_pk(float lo, float hi) { unsigned r; asm volatile("v_cvt_pk_bf16_f32 %0, %1, %2" : "=v"(r) : "v"(lo), "v"(hi)); return r; }
; __device__ __forceinline__ unsigned f2bf(float f) { unsigned u = __builtin_bit_cast(unsigned, f); return (u + 0x7fffu + ((u >> 16) & 1u)) >> 16; }
; __device__ __forceinline__ void scan_job(LAS unsigned char* lds, int b, int h, int dir, int layer, const bf16_t* P, const float* lbp, bf16_t* xc, bf16_t* ob) {
;     ...
;               for (int r = 0; r < 4; ++r) { const size_t row = dir ? row0 - r : row0 + r;
;                   if (dir == 0) xc[row * DM + 512 + col] = (bf16_t)f2bf(o[r]); else ob[row * 256 + col] = (bf16_t)f2bf(o[r]); } } }
;         { const f32x4 dec = *(const LAS f32x4*)(TOT + 16 * wid + 4 * lq);
;           const LAS unsigned char* ka = lds + S_K4T + (16 * wid + l15) * 144 + lq * 16; const bf16x8 k0 = *(const LAS bf16x8*)(ka), k1 = *(const LAS bf16x8*)(ka + 64);
; #pragma unroll
;           for (int vj = 0; vj < 4; ++vj) { const LAS unsigned char* vb = lds + S_VT + (16 * vj + l15) * 144 + lq * 16;
;               f32x4 a = Sacc[vj] * dec;
;               a = __builtin_amdgcn_mfma_f32_16x16x32_bf16(k0, *(const LAS bf16x8*)(vb), a, 0, 0, 0);
;               a = __builtin_amdgcn_mfma_f32_16x16x32_bf16(k1, *(const LAS bf16x8*)(vb + 64), a, 0, 0, 0);
;               Sacc[vj] = a; } }
;         __syncthreads();
; #pragma unroll
;         for (int vj = 0; vj < 4; ++vj) { u32x2 w; w.x = cvt_pk(Sacc[vj][0], Sacc[vj][1]); w.y = cvt_pk(Sacc[vj][2], Sacc[vj][3]);
;             *(LAS u32x2*)(lds + S_ST + (16 * vj + l15) * 272 + (16 * wid + 4 * lq) * 2) = w; }
.LBB0_1682:
	v_lshl_add_u64 v[34:35], v[68:69], 0, s[66:67]
	v_bfe_u32 v22, v23, 16, 1
	ds_read_b128 v[26:29], v107
	ds_read_b128 v[30:33], v118
	v_add3_u32 v48, v23, v22, s89
	v_lshl_add_u64 v[22:23], v[34:35], 0, v[76:77]
	ds_read_b128 v[34:37], v118 offset:64
	ds_read_b128 v[38:41], v119
	s_waitcnt lgkmcnt(3)
	v_mul_f32_e32 v8, v8, v28
	v_mul_f32_e32 v9, v9, v29
	v_mul_f32_e32 v6, v6, v26
	v_mul_f32_e32 v7, v7, v27
	ds_read_b128 v[42:45], v119 offset:64
	ds_read_b128 v[200:203], v119 offset:2304
	ds_read_b128 v[204:207], v119 offset:2368
	ds_read_b128 v[208:211], v119 offset:4608
	ds_read_b128 v[212:215], v119 offset:6976
	ds_read_b128 v[216:219], v119 offset:4672
	ds_read_b128 v[220:223], v119 offset:6912
	v_mul_f32_e32 v16, v16, v28
	v_mul_f32_e32 v17, v17, v29
	s_waitcnt lgkmcnt(7)
	v_mfma_f32_16x16x32_bf16 v[6:9], v[30:33], v[38:41], v[6:9]
	v_mul_f32_e32 v14, v14, v26
	v_mul_f32_e32 v15, v15, v27
	v_mul_f32_e32 v20, v20, v28
	v_mul_f32_e32 v21, v21, v29
	s_waitcnt lgkmcnt(6)
	v_mfma_f32_16x16x32_bf16 v[6:9], v[34:37], v[42:45], v[6:9]
	v_mul_f32_e32 v18, v18, v26
	v_mul_f32_e32 v19, v19, v27
	v_mul_f32_e32 v12, v12, v28
	v_mul_f32_e32 v13, v13, v29
	s_waitcnt lgkmcnt(5)
	v_mfma_f32_16x16x32_bf16 v[14:17], v[30:33], v[200:203], v[14:17]
	v_mul_f32_e32 v10, v10, v26
	v_mul_f32_e32 v11, v11, v27
	s_waitcnt lgkmcnt(4)
	v_mfma_f32_16x16x32_bf16 v[14:17], v[34:37], v[204:207], v[14:17]
	v_lshl_add_u64 v[46:47], v[22:23], 0, s[24:25]
	global_store_short_d16_hi v[46:47], v48, off offset:32
	s_waitcnt lgkmcnt(3)
	v_mfma_f32_16x16x32_bf16 v[18:21], v[30:33], v[208:211], v[18:21]
	v_bfe_u32 v46, v24, 16, 1
	v_add3_u32 v24, v24, v46, s89
	s_waitcnt lgkmcnt(0)
	v_mfma_f32_16x16x32_bf16 v[10:13], v[30:33], v[220:223], v[10:13]
	v_lshl_add_u64 v[46:47], v[22:23], 0, s[22:23]
	global_store_short_d16_hi v[46:47], v24, off offset:32
	v_bfe_u32 v24, v25, 16, 1
	v_mfma_f32_16x16x32_bf16 v[18:21], v[34:37], v[216:219], v[18:21]
	v_add3_u32 v24, v25, v24, s89
	v_lshl_add_u64 v[22:23], v[22:23], 0, s[20:21]
	global_store_short_d16_hi v[22:23], v24, off offset:32
	v_mfma_f32_16x16x32_bf16 v[10:13], v[34:37], v[212:215], v[10:13]
	s_barrier
	v_cvt_pk_bf16_f32 v22, v6, v7
	v_cvt_pk_bf16_f32 v23, v8, v9
	ds_write_b64 v120, v[22:23]
	v_cvt_pk_bf16_f32 v22, v14, v15
	v_cvt_pk_bf16_f32 v23, v16, v17
	ds_write_b64 v120, v[22:23] offset:4352
	v_cvt_pk_bf16_f32 v22, v18, v19
	v_cvt_pk_bf16_f32 v23, v20, v21
	s_cmp_lg_u32 s94, 36
	s_waitcnt vmcnt(23)
	v_mov_b32_e32 v47, v121
	s_waitcnt vmcnt(21)
	v_mov_b32_e32 v44, v122
	s_waitcnt vmcnt(19)
	v_mov_b32_e32 v43, v123
	s_waitcnt vmcnt(17)
	v_mov_b32_e32 v42, v124
	s_waitcnt vmcnt(15)
	v_mov_b32_e32 v41, v125
	s_waitcnt vmcnt(13)
	v_mov_b32_e32 v40, v126
	s_waitcnt vmcnt(11)
	v_mov_b32_e32 v39, v127
	s_waitcnt vmcnt(9)
	v_mov_b32_e32 v38, v128
	s_mov_b32 s66, s94
	ds_write_b64 v120, v[22:23] offset:8704
	v_cvt_pk_bf16_f32 v22, v10, v11
	v_cvt_pk_bf16_f32 v23, v12, v13
	ds_write_b64 v120, v[22:23] offset:13056
	s_cbranch_scc0 .LBB0_1662
